# NA main loop: 8 conditional bias LDS reads per score block batched behind one counted wait + select; ds_bpermute max-reductions replaced by permlane16/32 swaps (on top of v5)
# baseline (speedup 1.0000x reference)
.LBB0_758:
	s_add_i32 s13, s62, s12
	s_cmp_lt_u32 s12, 4
	s_cselect_b64 s[0:1], -1, 0
	s_and_b64 s[42:43], s[0:1], exec
	s_cselect_b32 s0, s12, s13
	s_lshl_b32 s0, s0, 6
	s_or_b32 s44, s0, 32
	s_ashr_i32 s45, s44, 31
	s_lshl_b64 s[44:45], s[44:45], 9
	s_ashr_i32 s1, s0, 31
	v_lshl_add_u64 v[80:81], v[188:189], 0, s[44:45]
	v_lshl_add_u64 v[84:85], s[0:1], 1, v[190:191]
	s_mov_b32 s0, 0x42000
	global_load_dwordx4 v[116:119], v[80:81], off
	global_load_dwordx4 v[120:123], v[80:81], off offset:64
	global_load_dwordx4 v[124:127], v[80:81], off offset:2048
	global_load_dwordx4 v[112:115], v[80:81], off offset:2112
	v_add_co_u32_e32 v80, vcc, s0, v84
	s_mov_b32 s0, 0x84000
	s_nop 0
	v_addc_co_u32_e32 v81, vcc, 0, v85, vcc
	v_add_co_u32_e32 v86, vcc, s0, v84
	s_mov_b32 s0, 0xc6000
	s_nop 0
	v_addc_co_u32_e32 v87, vcc, 0, v85, vcc
	global_load_dwordx4 v[88:91], v[84:85], off offset:64
	s_nop 0
	global_load_dwordx4 v[80:83], v[80:81], off offset:64
	v_add_co_u32_e32 v84, vcc, s0, v84
	s_waitcnt vmcnt(13)
	v_mfma_f32_16x16x32_bf16 v[148:151], v[96:99], v[36:39], 0
	v_addc_co_u32_e32 v85, vcc, 0, v85, vcc
	global_load_dwordx4 v[92:95], v[86:87], off offset:64
	s_nop 0
	global_load_dwordx4 v[84:87], v[84:85], off offset:64
	s_waitcnt vmcnt(14)
	v_mfma_f32_16x16x32_bf16 v[156:159], v[100:103], v[36:39], 0
	s_cmp_gt_u32 s12, 3
	s_cselect_b64 s[44:45], -1, 0
	v_cndmask_b32_e64 v0, 0, v233, s[44:45]
	s_waitcnt vmcnt(8)
	v_mfma_f32_16x16x32_bf16 v[152:155], v[104:107], v[48:51], v[148:151]
	s_add_i32 s96, 0, 0x1e000
	v_lshl_add_u32 v235, v0, 2, s96
	s_mov_b64 vcc, s[42:43]
	v_mfma_f32_16x16x32_bf16 v[148:151], v[108:111], v[48:51], v[156:159]
	s_cbranch_vccnz .LBB0_776
	s_nop 1
	v_lshl_add_u32 v182, v180, 2, v235
	ds_read_b32 v160, v182
	ds_read_b32 v156, v182 offset:16
	ds_read_b32 v161, v182 offset:4
	ds_read_b32 v157, v182 offset:20
	ds_read_b32 v162, v182 offset:8
	ds_read_b32 v158, v182 offset:24
	ds_read_b32 v163, v182 offset:12
	ds_read_b32 v159, v182 offset:28
	v_mov_b32_e32 v183, 0xff800000
	s_waitcnt lgkmcnt(7)
	v_add_f32_e32 v160, v152, v160
	v_cndmask_b32_e64 v160, v183, v160, s[46:47]
	s_waitcnt lgkmcnt(6)
	v_add_f32_e32 v156, v148, v156
	v_cndmask_b32_e64 v156, v183, v156, s[48:49]
	s_waitcnt lgkmcnt(5)
	v_add_f32_e32 v161, v153, v161
	v_cndmask_b32_e64 v161, v183, v161, s[50:51]
	s_waitcnt lgkmcnt(4)
	v_add_f32_e32 v157, v149, v157
	v_cndmask_b32_e64 v157, v183, v157, s[52:53]
	s_waitcnt lgkmcnt(3)
	v_add_f32_e32 v162, v154, v162
	v_cndmask_b32_e64 v162, v183, v162, s[38:39]
	s_waitcnt lgkmcnt(2)
	v_add_f32_e32 v158, v150, v158
	v_cndmask_b32_e64 v158, v183, v158, s[74:75]
	s_waitcnt lgkmcnt(1)
	v_add_f32_e32 v163, v155, v163
	v_cndmask_b32_e64 v163, v183, v163, s[4:5]
	s_waitcnt lgkmcnt(0)
	v_add_f32_e32 v159, v151, v159
	v_cndmask_b32_e64 v159, v183, v159, s[6:7]
	v_mov_b64_e32 v[152:153], v[160:161]
	v_mov_b64_e32 v[148:149], v[156:157]
	v_mov_b64_e32 v[154:155], v[162:163]
	v_mov_b64_e32 v[150:151], v[158:159]
.LBB0_776:
	s_nop 2
	v_max_f32_e32 v0, v153, v153
	v_max_f32_e32 v3, v152, v152
	v_max_f32_e32 v0, v3, v0
	v_max_f32_e32 v3, v155, v155
	v_max_f32_e32 v156, v154, v154
	v_max_f32_e32 v3, v156, v3
	v_max_f32_e32 v156, v151, v151
	v_max_f32_e32 v157, v150, v150
	v_max_f32_e32 v156, v157, v156
	v_max3_f32 v156, v148, v149, v156
	v_max3_f32 v0, v0, v3, v156
	v_mov_b32_e32 v3, v0
	s_nop 1
	v_permlane16_swap_b32_e32 v0, v3
	s_waitcnt lgkmcnt(0)
	v_max_f32_e32 v0, v0, v3
	v_mov_b32_e32 v3, v0
	s_nop 1
	v_permlane32_swap_b32_e32 v0, v3
	s_waitcnt lgkmcnt(0)
	v_max3_f32 v3, v173, v0, v3
	v_sub_f32_e32 v0, v173, v3
	v_exp_f32_e32 v0, v0
	s_nop 0
	v_cmp_neq_f32_e32 vcc, 1.0, v0
	s_cbranch_vccz .LBB0_850
	v_pk_mul_f32 v[158:159], v[146:147], v[0:1] op_sel_hi:[1,0]
	v_pk_mul_f32 v[156:157], v[144:145], v[0:1] op_sel_hi:[1,0]
	v_pk_mul_f32 v[170:171], v[134:135], v[0:1] op_sel_hi:[1,0]
	v_pk_mul_f32 v[168:169], v[132:133], v[0:1] op_sel_hi:[1,0]
	v_pk_mul_f32 v[178:179], v[138:139], v[0:1] op_sel_hi:[1,0]
	v_pk_mul_f32 v[176:177], v[136:137], v[0:1] op_sel_hi:[1,0]
	v_pk_mul_f32 v[174:175], v[142:143], v[0:1] op_sel_hi:[1,0]
	v_pk_mul_f32 v[172:173], v[140:141], v[0:1] op_sel_hi:[1,0]
	s_cbranch_execnz .LBB0_779

.LBB0_779:
	v_sub_f32_e32 v132, v152, v3
	v_exp_f32_e32 v136, v132
	v_sub_f32_e32 v132, v153, v3
	v_exp_f32_e32 v137, v132
	v_sub_f32_e32 v132, v154, v3
	v_exp_f32_e32 v138, v132
	v_sub_f32_e32 v132, v155, v3
	v_exp_f32_e32 v140, v132
	v_sub_f32_e32 v132, v148, v3
	v_exp_f32_e32 v139, v132
	v_sub_f32_e32 v132, v149, v3
	v_exp_f32_e32 v141, v132
	v_sub_f32_e32 v132, v150, v3
	v_exp_f32_e32 v142, v132
	v_sub_f32_e32 v132, v151, v3
	v_exp_f32_e32 v143, v132
	v_cvt_pk_bf16_f32 v132, v136, v137
	v_cvt_pk_bf16_f32 v133, v138, v140
	v_cvt_pk_bf16_f32 v134, v139, v141
	v_cvt_pk_bf16_f32 v135, v142, v143
	v_readlane_b32 s0, v252, 14
	v_readlane_b32 s1, v252, 15
	v_mfma_f32_16x16x32_bf16 v[160:163], v[68:71], v[132:135], v[156:159]
	s_and_b64 s[0:1], s[0:1], s[44:45]
	v_cndmask_b32_e64 v144, 0, v231, s[44:45]
	s_and_b64 vcc, exec, s[0:1]
	v_mfma_f32_16x16x32_bf16 v[156:159], v[76:79], v[132:135], v[168:171]
	v_mfma_f32_16x16x32_bf16 v[148:151], v[64:67], v[132:135], v[176:179]
	v_mfma_f32_16x16x32_bf16 v[152:155], v[72:75], v[132:135], v[172:175]
	v_cndmask_b32_e64 v132, 0, 1, s[44:45]
	s_nop 0
	v_lshl_add_u32 v176, v144, 2, s96
	v_cmp_ne_u32_e64 s[42:43], 1, v132
	s_cbranch_vccnz .LBB0_802
	v_mfma_f32_16x16x32_bf16 v[96:99], v[96:99], v[44:47], 0
	s_and_b64 vcc, exec, s[42:43]
	v_mfma_f32_16x16x32_bf16 v[128:131], v[100:103], v[44:47], 0
	v_mfma_f32_16x16x32_bf16 v[100:103], v[104:107], v[40:43], v[96:99]
	v_mfma_f32_16x16x32_bf16 v[96:99], v[108:111], v[40:43], v[128:131]
	s_cbranch_vccnz .LBB0_798
	v_lshl_add_u32 v182, v180, 2, v176
	ds_read_b32 v108, v182
	ds_read_b32 v104, v182 offset:16
	ds_read_b32 v109, v182 offset:4
	ds_read_b32 v105, v182 offset:20
	ds_read_b32 v110, v182 offset:8
	ds_read_b32 v106, v182 offset:24
	ds_read_b32 v111, v182 offset:12
	ds_read_b32 v107, v182 offset:28
	v_mov_b32_e32 v183, 0xff800000
	s_waitcnt lgkmcnt(7)
	v_add_f32_e32 v108, v100, v108
	v_cndmask_b32_e64 v108, v183, v108, s[8:9]
	s_waitcnt lgkmcnt(6)
	v_add_f32_e32 v104, v96, v104
	v_cndmask_b32_e64 v104, v183, v104, s[10:11]
	s_waitcnt lgkmcnt(5)
	v_add_f32_e32 v109, v101, v109
	v_cndmask_b32_e64 v109, v183, v109, s[34:35]
	s_waitcnt lgkmcnt(4)
	v_add_f32_e32 v105, v97, v105
	v_cndmask_b32_e64 v105, v183, v105, s[36:37]
	s_waitcnt lgkmcnt(3)
	v_add_f32_e32 v110, v102, v110
	v_cndmask_b32_e64 v110, v183, v110, s[56:57]
	s_waitcnt lgkmcnt(2)
	v_add_f32_e32 v106, v98, v106
	v_cndmask_b32_e64 v106, v183, v106, s[22:23]
	s_waitcnt lgkmcnt(1)
	v_add_f32_e32 v111, v103, v111
	v_cndmask_b32_e64 v111, v183, v111, s[84:85]
	s_waitcnt lgkmcnt(0)
	v_add_f32_e32 v107, v99, v107
	v_cndmask_b32_e64 v107, v183, v107, s[86:87]
	v_mov_b64_e32 v[100:101], v[108:109]
	v_mov_b64_e32 v[96:97], v[104:105]
	v_mov_b64_e32 v[102:103], v[110:111]
	v_mov_b64_e32 v[98:99], v[106:107]
.LBB0_798:
	s_nop 5
	v_max_f32_e32 v104, v101, v101
	v_max_f32_e32 v105, v100, v100
	v_max_f32_e32 v104, v105, v104
	v_max_f32_e32 v105, v103, v103
	v_max_f32_e32 v106, v102, v102
	v_max_f32_e32 v105, v106, v105
	v_max_f32_e32 v106, v99, v99
	v_max_f32_e32 v107, v98, v98
	v_max_f32_e32 v106, v107, v106
	v_max3_f32 v106, v96, v97, v106
	v_max3_f32 v104, v104, v105, v106
	v_mov_b32_e32 v105, v104
	s_nop 1
	v_permlane16_swap_b32_e32 v104, v105
	s_waitcnt lgkmcnt(0)
	v_max_f32_e32 v104, v104, v105
	v_mov_b32_e32 v105, v104
	s_nop 1
	v_permlane32_swap_b32_e32 v104, v105
	s_waitcnt lgkmcnt(0)
	v_max3_f32 v172, v2, v104, v105
	v_sub_f32_e32 v2, v2, v172
	v_exp_f32_e32 v2, v2
	s_nop 0
	v_cmp_neq_f32_e32 vcc, 1.0, v2
	s_cbranch_vccz .LBB0_852
	v_pk_mul_f32 v[134:135], v[54:55], v[2:3] op_sel_hi:[1,0]
	v_pk_mul_f32 v[132:133], v[52:53], v[2:3] op_sel_hi:[1,0]
	v_pk_mul_f32 v[130:131], v[58:59], v[2:3] op_sel_hi:[1,0]
	v_pk_mul_f32 v[128:129], v[56:57], v[2:3] op_sel_hi:[1,0]
	v_pk_mul_f32 v[110:111], v[62:63], v[2:3] op_sel_hi:[1,0]
	v_pk_mul_f32 v[108:109], v[60:61], v[2:3] op_sel_hi:[1,0]
	v_pk_mul_f32 v[106:107], v[166:167], v[2:3] op_sel_hi:[1,0]
	v_pk_mul_f32 v[104:105], v[164:165], v[2:3] op_sel_hi:[1,0]
	s_cbranch_execnz .LBB0_801

.LBB0_803:
	v_readlane_b32 s0, v251, 23
	v_readlane_b32 s1, v251, 24
	s_and_b64 s[44:45], s[0:1], s[44:45]
	s_add_i32 s12, s12, 1
	v_readlane_b32 s0, v252, 24
	s_min_i32 s0, s12, s0
	s_cmp_gt_u32 s0, 3
	s_cselect_b32 s1, s62, 0
	v_add_f32_e32 v2, v136, v137
	v_add_f32_e32 v64, v138, v140
	s_add_i32 s13, s1, s0
	v_add_f32_e32 v2, v2, v64
	s_lshl_b32 s14, s13, 6
	v_fmac_f32_e32 v2, v234, v0
	v_add_f32_e32 v0, v139, v141
	v_add_f32_e32 v64, v142, v143
	s_lshl_b64 s[0:1], s[14:15], 9
	s_lshl_b32 s14, s13, 7
	v_add_f32_e32 v0, v0, v64
	v_lshl_add_u64 v[64:65], v[188:189], 0, s[0:1]
	v_lshl_add_u64 v[72:73], v[190:191], 0, s[14:15]
	global_load_dwordx4 v[96:99], v[64:65], off
	global_load_dwordx4 v[100:103], v[64:65], off offset:2048
	global_load_dwordx4 v[104:107], v[64:65], off offset:64
	global_load_dwordx4 v[108:111], v[64:65], off offset:2112
	v_add_co_u32_e32 v64, vcc, 0x42000, v72
	global_load_dwordx4 v[68:71], v[72:73], off
	s_nop 0
	v_addc_co_u32_e32 v65, vcc, 0, v73, vcc
	global_load_dwordx4 v[76:79], v[64:65], off
	v_add_co_u32_e32 v64, vcc, 0x84000, v72
	v_add_f32_e32 v2, v0, v2
	s_nop 0
	v_addc_co_u32_e32 v65, vcc, 0, v73, vcc
	v_add_co_u32_e32 v72, vcc, 0xc6000, v72
	global_load_dwordx4 v[64:67], v[64:65], off
	s_nop 0
	v_addc_co_u32_e32 v73, vcc, 0, v73, vcc
	global_load_dwordx4 v[72:75], v[72:73], off
	s_mov_b64 s[90:91], -1
	s_andn2_b64 vcc, exec, s[44:45]
	s_cbranch_vccz .LBB0_825
	s_waitcnt vmcnt(15)
	v_mfma_f32_16x16x32_bf16 v[132:135], v[116:119], v[36:39], 0
	s_and_b64 vcc, exec, s[42:43]
	s_waitcnt vmcnt(13)
	v_mfma_f32_16x16x32_bf16 v[140:143], v[124:127], v[36:39], 0
	v_mfma_f32_16x16x32_bf16 v[136:139], v[120:123], v[48:51], v[132:135]
	s_waitcnt vmcnt(12)
	v_mfma_f32_16x16x32_bf16 v[132:135], v[112:115], v[48:51], v[140:143]
	s_cbranch_vccnz .LBB0_822
	s_nop 3
	v_lshl_add_u32 v182, v180, 2, v235
	ds_read_b32 v144, v182 offset:128
	ds_read_b32 v140, v182 offset:144
	ds_read_b32 v145, v182 offset:132
	ds_read_b32 v141, v182 offset:148
	ds_read_b32 v146, v182 offset:136
	ds_read_b32 v142, v182 offset:152
	ds_read_b32 v147, v182 offset:140
	ds_read_b32 v143, v182 offset:156
	v_mov_b32_e32 v183, 0xff800000
	s_waitcnt lgkmcnt(7)
	v_add_f32_e32 v144, v136, v144
	v_cndmask_b32_e64 v144, v183, v144, s[64:65]
	s_waitcnt lgkmcnt(6)
	v_add_f32_e32 v140, v132, v140
	v_cndmask_b32_e64 v140, v183, v140, s[72:73]
	s_waitcnt lgkmcnt(5)
	v_add_f32_e32 v145, v137, v145
	v_cndmask_b32_e64 v145, v183, v145, s[26:27]
	s_waitcnt lgkmcnt(4)
	v_add_f32_e32 v141, v133, v141
	v_cndmask_b32_e64 v141, v183, v141, s[24:25]
	s_waitcnt lgkmcnt(3)
	v_add_f32_e32 v146, v138, v146
	v_cndmask_b32_e64 v146, v183, v146, s[28:29]
	s_waitcnt lgkmcnt(2)
	v_add_f32_e32 v142, v134, v142
	v_cndmask_b32_e64 v142, v183, v142, s[30:31]
	s_waitcnt lgkmcnt(1)
	v_add_f32_e32 v147, v139, v147
	v_cndmask_b32_e64 v147, v183, v147, s[70:71]
	s_waitcnt lgkmcnt(0)
	v_add_f32_e32 v143, v135, v143
	v_cndmask_b32_e64 v143, v183, v143, s[40:41]
	v_mov_b64_e32 v[136:137], v[144:145]
	v_mov_b64_e32 v[132:133], v[140:141]
	v_mov_b64_e32 v[138:139], v[146:147]
	v_mov_b64_e32 v[134:135], v[142:143]
.LBB0_822:
	s_nop 4
	v_max_f32_e32 v0, v137, v137
	v_max_f32_e32 v140, v136, v136
	v_max_f32_e32 v0, v140, v0
	v_max_f32_e32 v140, v139, v139
	v_max_f32_e32 v141, v138, v138
	v_max_f32_e32 v140, v141, v140
	v_max_f32_e32 v141, v135, v135
	v_max_f32_e32 v142, v134, v134
	v_max_f32_e32 v141, v142, v141
	v_max3_f32 v141, v132, v133, v141
	v_max3_f32 v0, v0, v140, v141
	v_mov_b32_e32 v140, v0
	s_nop 1
	v_permlane16_swap_b32_e32 v0, v140
	v_mov_b64_e32 v[166:167], v[150:151]
	v_mov_b64_e32 v[170:171], v[158:159]
	v_mov_b64_e32 v[144:145], v[160:161]
	v_mov_b64_e32 v[164:165], v[148:149]
	s_waitcnt lgkmcnt(0)
	v_max_f32_e32 v0, v0, v140
	v_mov_b32_e32 v140, v0
	s_nop 1
	v_permlane32_swap_b32_e32 v0, v140
	v_mov_b64_e32 v[168:169], v[156:157]
	v_mov_b64_e32 v[146:147], v[162:163]
	s_waitcnt lgkmcnt(0)
	v_max3_f32 v173, v3, v0, v140
	v_sub_f32_e32 v0, v3, v173
	v_exp_f32_e32 v0, v0
	v_mov_b64_e32 v[140:141], v[152:153]
	v_mov_b64_e32 v[142:143], v[154:155]
	v_cmp_neq_f32_e32 vcc, 1.0, v0
	s_cbranch_vccz .LBB0_824
	v_pk_mul_f32 v[146:147], v[162:163], v[0:1] op_sel_hi:[1,0]
	v_pk_mul_f32 v[144:145], v[160:161], v[0:1] op_sel_hi:[1,0]
	v_pk_mul_f32 v[170:171], v[158:159], v[0:1] op_sel_hi:[1,0]
	v_pk_mul_f32 v[168:169], v[156:157], v[0:1] op_sel_hi:[1,0]
	v_pk_mul_f32 v[166:167], v[150:151], v[0:1] op_sel_hi:[1,0]
	v_pk_mul_f32 v[164:165], v[148:149], v[0:1] op_sel_hi:[1,0]
	v_pk_mul_f32 v[142:143], v[154:155], v[0:1] op_sel_hi:[1,0]
	v_pk_mul_f32 v[140:141], v[152:153], v[0:1] op_sel_hi:[1,0]

.LBB0_827:
	s_waitcnt vmcnt(15)
	v_mfma_f32_16x16x32_bf16 v[116:119], v[116:119], v[44:47], 0
	v_readlane_b32 s90, v254, 8
	s_and_b64 vcc, exec, s[42:43]
	v_readlane_b32 s91, v254, 9
	s_waitcnt vmcnt(13)
	v_mfma_f32_16x16x32_bf16 v[124:127], v[124:127], v[44:47], 0
	v_mfma_f32_16x16x32_bf16 v[116:119], v[120:123], v[40:43], v[116:119]
	s_waitcnt vmcnt(12)
	v_mfma_f32_16x16x32_bf16 v[112:115], v[112:115], v[40:43], v[124:127]
	s_cbranch_vccnz .LBB0_845
	s_nop 1
	v_lshl_add_u32 v182, v180, 2, v176
	ds_read_b32 v124, v182 offset:128
	ds_read_b32 v120, v182 offset:144
	ds_read_b32 v125, v182 offset:132
	ds_read_b32 v121, v182 offset:148
	ds_read_b32 v126, v182 offset:136
	ds_read_b32 v122, v182 offset:152
	ds_read_b32 v127, v182 offset:140
	ds_read_b32 v123, v182 offset:156
	v_mov_b32_e32 v183, 0xff800000
	s_waitcnt lgkmcnt(7)
	v_add_f32_e32 v124, v116, v124
	v_cndmask_b32_e64 v124, v183, v124, s[76:77]
	s_waitcnt lgkmcnt(6)
	v_add_f32_e32 v120, v112, v120
	v_cndmask_b32_e64 v120, v183, v120, s[78:79]
	s_waitcnt lgkmcnt(5)
	v_add_f32_e32 v125, v117, v125
	v_cndmask_b32_e64 v125, v183, v125, s[80:81]
	s_waitcnt lgkmcnt(4)
	v_add_f32_e32 v121, v113, v121
	v_cndmask_b32_e64 v121, v183, v121, s[82:83]
	s_waitcnt lgkmcnt(3)
	v_add_f32_e32 v126, v118, v126
	v_cndmask_b32_e64 v126, v183, v126, s[88:89]
	s_waitcnt lgkmcnt(2)
	v_add_f32_e32 v122, v114, v122
	v_cndmask_b32_e64 v122, v183, v122, s[2:3]
	s_waitcnt lgkmcnt(1)
	v_add_f32_e32 v127, v119, v127
	v_cndmask_b32_e64 v127, v183, v127, s[66:67]
	s_waitcnt lgkmcnt(0)
	v_add_f32_e32 v123, v115, v123
	v_cndmask_b32_e64 v123, v183, v123, s[16:17]
	v_mov_b64_e32 v[116:117], v[124:125]
	v_mov_b64_e32 v[112:113], v[120:121]
	v_mov_b64_e32 v[118:119], v[126:127]
	v_mov_b64_e32 v[114:115], v[122:123]
.LBB0_845:
	s_nop 4
	v_max_f32_e32 v0, v117, v117
	v_max_f32_e32 v2, v116, v116
	v_max_f32_e32 v0, v2, v0
	v_max_f32_e32 v2, v119, v119
	v_max_f32_e32 v3, v118, v118
	v_max_f32_e32 v2, v3, v2
	v_max_f32_e32 v3, v115, v115
	v_max_f32_e32 v120, v114, v114
	v_max_f32_e32 v3, v120, v3
	v_max3_f32 v3, v112, v113, v3
	v_max3_f32 v0, v0, v2, v3
	v_mov_b32_e32 v2, v0
	s_nop 1
	v_permlane16_swap_b32_e32 v0, v2
	s_waitcnt lgkmcnt(0)
	v_max_f32_e32 v0, v0, v2
	v_mov_b32_e32 v2, v0
	s_nop 1
	v_permlane32_swap_b32_e32 v0, v2
	s_waitcnt lgkmcnt(0)
	v_max3_f32 v2, v172, v0, v2
	v_sub_f32_e32 v0, v172, v2
	v_exp_f32_e32 v0, v0
	s_nop 0
	v_cmp_neq_f32_e32 vcc, 1.0, v0
	s_cbranch_vccz .LBB0_851
	v_pk_mul_f32 v[154:155], v[54:55], v[0:1] op_sel_hi:[1,0]
	v_pk_mul_f32 v[152:153], v[52:53], v[0:1] op_sel_hi:[1,0]
	v_pk_mul_f32 v[150:151], v[58:59], v[0:1] op_sel_hi:[1,0]
	v_pk_mul_f32 v[148:149], v[56:57], v[0:1] op_sel_hi:[1,0]
	v_pk_mul_f32 v[126:127], v[62:63], v[0:1] op_sel_hi:[1,0]
	v_pk_mul_f32 v[124:125], v[60:61], v[0:1] op_sel_hi:[1,0]
	v_pk_mul_f32 v[122:123], v[130:131], v[0:1] op_sel_hi:[1,0]
	v_pk_mul_f32 v[120:121], v[128:129], v[0:1] op_sel_hi:[1,0]
	s_cbranch_execnz .LBB0_848
